# v25 + pool_item projection/epilogue rewritten: unrolled wave-uniform tile loop, channel scale loaded once per item, cheap store addressing
# speedup vs baseline: 1.0109x; 1.0067x over previous
; __device__ __forceinline__ bf16_t f2bf(float f) { unsigned u = __float_as_uint(f); u += 0x7FFFu + ((u >> 16) & 1u); return (bf16_t)(u >> 16); }
; __device__ __forceinline__ void pool_item(const Bufs& B, int l, int s, int it, unsigned char* shm, const PoolRegs& R) {
;     ...
; #pragma unroll 4
;         for (int q = 0; q < 16; ++q) {
;             const int t = t0 + q, tg = s * 2048 + tl0 + t;
;             const float cur = raw[(16 + t) * 128 + c];
;             run += cur;
;             const int cnt = (tg + 1) < win ? (tg + 1) : win;
;             dA[t * 136 + c] = f2bf(run / (float)cnt - cur);
;             run -= raw[(16 + t - win + 1) * 128 + c];
;         }
.LBB0_569:
	v_add_u32_e32 v36, s3, v28
	ds_read2st64_b32 v[32:33], v29 offset1:2
	v_add_u32_e32 v34, 1, v36
	v_min_i32_e32 v34, s2, v34
	v_cvt_f32_i32_e32 v34, v34
	s_add_i32 s3, s3, 4
	s_waitcnt lgkmcnt(0)
	v_add_f32_e32 v31, v31, v32
	s_cmp_eq_u32 s3, 16
	v_div_scale_f32 v35, s[36:37], v34, v34, v31
	v_rcp_f32_e32 v37, v35
	s_nop 0
	v_fma_f32 v38, -v35, v37, 1.0
	v_fmac_f32_e32 v37, v38, v37
	v_div_scale_f32 v38, vcc, v31, v34, v31
	v_mul_f32_e32 v39, v38, v37
	v_fma_f32 v52, -v35, v39, v38
	v_fmac_f32_e32 v39, v52, v37
	v_fma_f32 v35, -v35, v39, v38
	v_div_fmas_f32 v35, v35, v37, v39
	v_div_fixup_f32 v34, v35, v34, v31
	v_sub_f32_e32 v32, v34, v32
	v_bfe_u32 v34, v32, 16, 1
	v_add_u32_e32 v37, s22, v29
	v_add3_u32 v32, v32, v34, s78
	ds_read2st64_b32 v[34:35], v37 offset0:2 offset1:4
	ds_write_b16_d16_hi v30, v32
	v_add_u32_e32 v32, 2, v36
	v_min_i32_e32 v32, s2, v32
	v_cvt_f32_i32_e32 v32, v32
	s_waitcnt lgkmcnt(1)
	v_sub_f32_e32 v31, v31, v34
	v_add_f32_e32 v31, v31, v33
	v_div_scale_f32 v34, s[36:37], v32, v32, v31
	v_rcp_f32_e32 v38, v34
	s_nop 0
	v_fma_f32 v39, -v34, v38, 1.0
	v_fmac_f32_e32 v38, v39, v38
	v_div_scale_f32 v39, vcc, v31, v32, v31
	v_mul_f32_e32 v52, v39, v38
	v_fma_f32 v53, -v34, v52, v39
	v_fmac_f32_e32 v52, v53, v38
	v_fma_f32 v34, -v34, v52, v39
	v_div_fmas_f32 v34, v34, v38, v52
	v_div_fixup_f32 v32, v34, v32, v31
	v_sub_f32_e32 v32, v32, v33
	v_bfe_u32 v33, v32, 16, 1
	v_add3_u32 v32, v32, v33, s78
	ds_write_b16_d16_hi v30, v32 offset:272
	ds_read2st64_b32 v[32:33], v29 offset0:4 offset1:6
	v_add_u32_e32 v34, 3, v36
	v_min_i32_e32 v34, s2, v34
	v_cvt_f32_i32_e32 v34, v34
	v_sub_f32_e32 v31, v31, v35
	s_waitcnt lgkmcnt(0)
	v_add_f32_e32 v31, v31, v32
	v_add_u32_e32 v29, 0x800, v29
	v_div_scale_f32 v35, s[36:37], v34, v34, v31
	v_rcp_f32_e32 v38, v35
	s_nop 0
	v_fma_f32 v39, -v35, v38, 1.0
	v_fmac_f32_e32 v38, v39, v38
	v_div_scale_f32 v39, vcc, v31, v34, v31
	v_mul_f32_e32 v52, v39, v38
	v_fma_f32 v53, -v35, v52, v39
	v_fmac_f32_e32 v52, v53, v38
	v_fma_f32 v35, -v35, v52, v39
	v_div_fmas_f32 v35, v35, v38, v52
	v_div_fixup_f32 v34, v35, v34, v31
	v_sub_f32_e32 v32, v34, v32
	v_bfe_u32 v34, v32, 16, 1
	v_add3_u32 v32, v32, v34, s78
	ds_read2st64_b32 v[34:35], v37 offset0:6 offset1:8
	ds_write_b16_d16_hi v30, v32 offset:544
	v_add_u32_e32 v32, 4, v36
	v_min_i32_e32 v32, s2, v32
	v_cvt_f32_i32_e32 v32, v32
	s_waitcnt lgkmcnt(1)
	v_sub_f32_e32 v31, v31, v34
	v_add_f32_e32 v31, v31, v33
	v_div_scale_f32 v34, s[36:37], v32, v32, v31
	v_rcp_f32_e32 v36, v34
	s_nop 0
	v_fma_f32 v37, -v34, v36, 1.0
	v_fmac_f32_e32 v36, v37, v36
	v_div_scale_f32 v37, vcc, v31, v32, v31
	v_mul_f32_e32 v38, v37, v36
	v_fma_f32 v39, -v34, v38, v37
	v_fmac_f32_e32 v38, v39, v36
	v_fma_f32 v34, -v34, v38, v37
	v_div_fmas_f32 v34, v34, v36, v38
	v_div_fixup_f32 v32, v34, v32, v31
	v_sub_f32_e32 v32, v32, v33
	v_bfe_u32 v33, v32, 16, 1
	v_add3_u32 v32, v32, v33, s78
	ds_write_b16_d16_hi v30, v32 offset:816
	v_sub_f32_e32 v31, v31, v35
	v_add_u32_e32 v30, 0x440, v30
	s_cbranch_scc0 .LBB0_569
	s_waitcnt lgkmcnt(0)
	s_barrier
; __device__ __forceinline__ bf16_t f2bf(float f) { unsigned u = __float_as_uint(f); u += 0x7FFFu + ((u >> 16) & 1u); return (bf16_t)(u >> 16); }
; __device__ __forceinline__ void pool_item(const Bufs& B, int l, int s, int it, unsigned char* shm, const PoolRegs& R) {
;     ...
;     const float* scale = IN(5) + l * 512 + g * 128;
;     for (int tile = wid; tile < 32; tile += 8) {
;         const int tm = tile >> 3, tn = tile & 7;
;         const f32x4 acc = mma_tile_pre<4>(dA + tm * 16 * 136, 136, pf, lane);
;         const int col = tn * 16 + (lane & 15);
;         const float sc = scale[col];
; #pragma unroll
;         for (int j = 0; j < 4; ++j) { const int row = tm * 16 + (lane >> 4) * 4 + j; B.br[(size_t)(m0 + row) * 512 + g * 128 + col] = f2bf(acc[j] * sc); }
;     }
	s_load_dwordx2 s[22:23], s[0:1], 40
	v_and_b32_e32 v43, 15, v179
	v_bfe_u32 v176, v179, 4, 2
	v_lshrrev_b32_e32 v45, 6, v179
	v_mul_u32_u24_e32 v52, 0x110, v43
	v_lshl_add_u32 v52, v176, 4, v52
	v_readfirstlane_b32 s36, v45
	s_waitcnt lgkmcnt(0)
	s_and_b32 s30, s34, 0xffffffc0
	s_add_u32 s22, s22, s18
	s_addc_u32 s23, s23, s19
	s_lshl_b32 s34, s35, 2
	s_add_u32 s22, s22, s34
	s_addc_u32 s23, s23, 0
	s_lshl_b32 s34, s35, 1
	s_add_u32 s34, s40, s34
	s_addc_u32 s35, s41, 0
	s_lshl_b32 s37, s30, 10
	s_add_u32 s34, s34, s37
	s_addc_u32 s35, s35, 0
	v_lshl_add_u32 v53, s36, 4, v43
	v_lshlrev_b32_e32 v54, 2, v53
	global_load_dword v45, v54, s[22:23]
	v_lshlrev_b32_e32 v53, 1, v53
	v_lshl_add_u32 v53, v176, 12, v53
	ds_read_b128 v[28:31], v52 offset:40960
	ds_read_b128 v[32:35], v52 offset:41024
	ds_read_b128 v[36:39], v52 offset:41088
	s_waitcnt vmcnt(0) lgkmcnt(0)
	v_mfma_f32_16x16x32_bf16 v[28:31], v[28:31], v[12:15], 0
	v_mfma_f32_16x16x32_bf16 v[28:31], v[32:35], v[16:19], v[28:31]
	ds_read_b128 v[32:35], v52 offset:41152
	v_mfma_f32_16x16x32_bf16 v[28:31], v[36:39], v[20:23], v[28:31]
	v_mov_b32_e32 v54, v53
	s_waitcnt lgkmcnt(0)
	v_mfma_f32_16x16x32_bf16 v[28:31], v[32:35], v[24:27], v[28:31]
	s_nop 7
	s_nop 1
	v_mul_f32_e32 v36, v45, v28
	v_mul_f32_e32 v37, v45, v29
	v_mul_f32_e32 v38, v45, v30
	v_mul_f32_e32 v39, v45, v31
	v_bfe_u32 v32, v36, 16, 1
	v_bfe_u32 v33, v37, 16, 1
	v_bfe_u32 v34, v38, 16, 1
	v_bfe_u32 v35, v39, 16, 1
	v_add3_u32 v36, v36, v32, s78
	global_store_short_d16_hi v54, v36, s[34:35]
	v_add3_u32 v37, v37, v33, s78
	global_store_short_d16_hi v54, v37, s[34:35] offset:1024
	v_add3_u32 v38, v38, v34, s78
	global_store_short_d16_hi v54, v38, s[34:35] offset:2048
	v_add3_u32 v39, v39, v35, s78
	global_store_short_d16_hi v54, v39, s[34:35] offset:3072
	ds_read_b128 v[28:31], v52 offset:45312
	ds_read_b128 v[32:35], v52 offset:45376
	ds_read_b128 v[36:39], v52 offset:45440
	s_waitcnt lgkmcnt(0)
	v_mfma_f32_16x16x32_bf16 v[28:31], v[28:31], v[12:15], 0
	v_mfma_f32_16x16x32_bf16 v[28:31], v[32:35], v[16:19], v[28:31]
	ds_read_b128 v[32:35], v52 offset:45504
	v_mfma_f32_16x16x32_bf16 v[28:31], v[36:39], v[20:23], v[28:31]
	v_add_u32_e32 v54, 0x4000, v53
	s_waitcnt lgkmcnt(0)
	v_mfma_f32_16x16x32_bf16 v[28:31], v[32:35], v[24:27], v[28:31]
	s_nop 7
	s_nop 1
	v_mul_f32_e32 v36, v45, v28
	v_mul_f32_e32 v37, v45, v29
	v_mul_f32_e32 v38, v45, v30
	v_mul_f32_e32 v39, v45, v31
	v_bfe_u32 v32, v36, 16, 1
	v_bfe_u32 v33, v37, 16, 1
	v_bfe_u32 v34, v38, 16, 1
	v_bfe_u32 v35, v39, 16, 1
	v_add3_u32 v36, v36, v32, s78
	global_store_short_d16_hi v54, v36, s[34:35]
	v_add3_u32 v37, v37, v33, s78
	global_store_short_d16_hi v54, v37, s[34:35] offset:1024
	v_add3_u32 v38, v38, v34, s78
	global_store_short_d16_hi v54, v38, s[34:35] offset:2048
	v_add3_u32 v39, v39, v35, s78
	global_store_short_d16_hi v54, v39, s[34:35] offset:3072
	ds_read_b128 v[28:31], v52 offset:49664
	ds_read_b128 v[32:35], v52 offset:49728
	ds_read_b128 v[36:39], v52 offset:49792
	s_waitcnt lgkmcnt(0)
	v_mfma_f32_16x16x32_bf16 v[28:31], v[28:31], v[12:15], 0
	v_mfma_f32_16x16x32_bf16 v[28:31], v[32:35], v[16:19], v[28:31]
	ds_read_b128 v[32:35], v52 offset:49856
	v_mfma_f32_16x16x32_bf16 v[28:31], v[36:39], v[20:23], v[28:31]
	v_add_u32_e32 v54, 0x8000, v53
	s_waitcnt lgkmcnt(0)
	v_mfma_f32_16x16x32_bf16 v[28:31], v[32:35], v[24:27], v[28:31]
	s_nop 7
	s_nop 1
	v_mul_f32_e32 v36, v45, v28
	v_mul_f32_e32 v37, v45, v29
	v_mul_f32_e32 v38, v45, v30
	v_mul_f32_e32 v39, v45, v31
	v_bfe_u32 v32, v36, 16, 1
	v_bfe_u32 v33, v37, 16, 1
	v_bfe_u32 v34, v38, 16, 1
	v_bfe_u32 v35, v39, 16, 1
	v_add3_u32 v36, v36, v32, s78
	global_store_short_d16_hi v54, v36, s[34:35]
	v_add3_u32 v37, v37, v33, s78
	global_store_short_d16_hi v54, v37, s[34:35] offset:1024
	v_add3_u32 v38, v38, v34, s78
	global_store_short_d16_hi v54, v38, s[34:35] offset:2048
	v_add3_u32 v39, v39, v35, s78
	global_store_short_d16_hi v54, v39, s[34:35] offset:3072
	ds_read_b128 v[28:31], v52 offset:54016
	ds_read_b128 v[32:35], v52 offset:54080
	ds_read_b128 v[36:39], v52 offset:54144
	s_waitcnt lgkmcnt(0)
	v_mfma_f32_16x16x32_bf16 v[28:31], v[28:31], v[12:15], 0
	v_mfma_f32_16x16x32_bf16 v[28:31], v[32:35], v[16:19], v[28:31]
	ds_read_b128 v[32:35], v52 offset:54208
	v_mfma_f32_16x16x32_bf16 v[28:31], v[36:39], v[20:23], v[28:31]
	v_add_u32_e32 v54, 0xc000, v53
	s_waitcnt lgkmcnt(0)
	v_mfma_f32_16x16x32_bf16 v[28:31], v[32:35], v[24:27], v[28:31]
	s_nop 7
	s_nop 1
	v_mul_f32_e32 v36, v45, v28
	v_mul_f32_e32 v37, v45, v29
	v_mul_f32_e32 v38, v45, v30
	v_mul_f32_e32 v39, v45, v31
	v_bfe_u32 v32, v36, 16, 1
	v_bfe_u32 v33, v37, 16, 1
	v_bfe_u32 v34, v38, 16, 1
	v_bfe_u32 v35, v39, 16, 1
	v_add3_u32 v36, v36, v32, s78
	global_store_short_d16_hi v54, v36, s[34:35]
	v_add3_u32 v37, v37, v33, s78
	global_store_short_d16_hi v54, v37, s[34:35] offset:1024
	v_add3_u32 v38, v38, v34, s78
	global_store_short_d16_hi v54, v38, s[34:35] offset:2048
	v_add3_u32 v39, v39, v35, s78
	global_store_short_d16_hi v54, v39, s[34:35] offset:3072
	s_mov_b64 s[2:3], exec
	s_branch .LBB0_556
